# LRUC backward sweep: phase-B HSF+GATE loads issued in phase A right behind each tile's XR loads (stream in under the gate math)
# baseline (speedup 1.0000x reference)
; __device__ __forceinline__ unsigned f2bf(float f) { return pk2(f, 0.0f) & 0xffffu; }
; __device__ __forceinline__ float bflo(unsigned w) { return __uint_as_float(w << 16); }
; __device__ __forceinline__ float bfhi(unsigned w) { return __uint_as_float(w & 0xffff0000u); }
; __device__ __forceinline__ float sigmoidf_(float x) { return __builtin_amdgcn_rcpf(1.0f + __builtin_amdgcn_exp2f(x * -1.4426950408889634f)); }
; __device__ __forceinline__ f32x16 mfma32(bf16x8 a, bf16x8 b, f32x16 c) { return __builtin_amdgcn_mfma_f32_32x32x16_bf16(a, b, c, 0, 0, 0); }
; template <int DIR>
; __device__ __forceinline__ void lru_dir(const bf16_t* XR, const bf16_t* GATE, bf16_t* YP, u32x4* HSF, const bf16_t* bdw_dir, float bias_r, float bias_i, float sp,
;                                         int b, int n2, int lane, int wave, LAS float* xl) {
;     ...
;                     const u32x4 w0 = hp[0], w1 = hp[1];
;                     const unsigned hw[8] = {w0.x, w0.y, w0.z, w0.w, w1.x, w1.y, w1.z, w1.w};
;                     const bf16_t* gp = GATE + (size_t)(trow[k] + tau) * DM + chcol + 8 * hh;
;                     const bf16x8 G0 = *(const bf16x8*)gp, G1 = *(const bf16x8*)(gp + 16);
;                     f32x16 gv;
; #pragma unroll
;                     for (int r = 0; r < 16; ++r) gv[r] = 0.f;
;                     gv = mfma32(G0, I0, gv); gv = mfma32(G1, I1, gv);
;                     bf16_t* yp = YP + (size_t)(trow[k] + 16 * hh) * DM + chcol + e;
; #pragma unroll
;                     for (int r = 0; r < 16; ++r) { const float x = gv[r], u2 = 1.5957691216f * (x + 0.044715f * x * x * x);
;                         const float hf = (r & 1) ? bfhi(hw[r >> 1]) : bflo(hw[r >> 1]);
;                         const float y = (hf + hs[r]) * x * sigmoidf_(u2);
;                         yp[(size_t)r * DM] = (bf16_t)f2bf(y); }
.LBB0_46:
	s_waitcnt lgkmcnt(0)
	v_cndmask_b32_e64 v0, v170, v0, s[40:41]
	v_fmac_f32_e32 v31, v47, v0
	v_fmac_f32_e32 v30, v46, v31
	v_fmac_f32_e32 v29, v45, v30
	v_fmac_f32_e32 v28, v44, v29
	v_fmac_f32_e32 v27, v43, v28
	v_fmac_f32_e32 v26, v42, v27
	v_fmac_f32_e32 v25, v41, v26
	s_ashr_i32 s3, s2, 31
	v_fmac_f32_e32 v24, v40, v25
	s_lshl_b64 s[2:3], s[2:3], 16
	v_fmac_f32_e32 v33, v39, v24
	v_lshl_add_u64 v[0:1], v[112:113], 0, s[2:3]
	v_fmac_f32_e32 v32, v38, v33
	s_waitcnt vmcnt(16)
	v_mov_b32_e32 v16, v200
	v_mov_b32_e32 v17, v201
	v_mov_b32_e32 v18, v202
	v_mov_b32_e32 v19, v203
	v_mov_b32_e32 v20, v204
	v_mov_b32_e32 v21, v205
	v_mov_b32_e32 v22, v206
	v_mov_b32_e32 v23, v207
	v_lshlrev_b64 v[0:1], 11, v[144:145]
	v_fmac_f32_e32 v35, v37, v32
	v_lshl_add_u64 v[4:5], v[120:121], 0, v[0:1]
	v_fmac_f32_e32 v34, v36, v35
	v_mov_b32_e32 v0, v208
	v_mov_b32_e32 v1, v209
	v_mov_b32_e32 v2, v210
	v_mov_b32_e32 v3, v211
	v_mov_b32_e32 v36, v212
	v_mov_b32_e32 v37, v213
	v_mov_b32_e32 v38, v214
	v_mov_b32_e32 v39, v215
	v_fmac_f32_e32 v143, v161, v34
	v_fmac_f32_e32 v142, v160, v143
	v_fmac_f32_e32 v155, v127, v142
	v_fmac_f32_e32 v154, v126, v155
	s_movk_i32 s2, 0x1000
	v_mfma_f32_32x32x16_bf16 v[0:15], v[0:3], v[58:61], 0
	v_mfma_f32_32x32x16_bf16 v[0:15], v[36:39], v[62:65], v[0:15]
	v_lshlrev_b32_e32 v39, 16, v20
	v_or_b32_e32 v36, s37, v102
	v_add_f32_e32 v39, v154, v39
	v_ashrrev_i32_e32 v37, 31, v36
	v_lshlrev_b64 v[36:37], 11, v[36:37]
	v_lshl_add_u64 v[36:37], v[122:123], 0, v[36:37]
	v_and_b32_e32 v20, 0xffff0000, v20
	s_nop 4
	v_mul_f32_e32 v38, 0x3d372713, v0
	v_mul_f32_e32 v38, v0, v38
	v_fma_f32 v38, v0, v38, v0
	v_mul_f32_e32 v38, 0x3fcc422a, v38
	v_mul_f32_e32 v38, 0xbfb8aa3b, v38
	v_exp_f32_e32 v38, v38
	v_mul_f32_e32 v0, v39, v0
	v_add_f32_e32 v20, v155, v20
	v_add_f32_e32 v38, 1.0, v38
	v_rcp_f32_e32 v38, v38
	s_nop 0
	v_mul_f32_e32 v0, v0, v38
	v_cvt_pk_bf16_f32 v0, v0, v49
	global_store_short v[36:37], v0, off
	v_mul_f32_e32 v0, 0x3d372713, v1
	v_mul_f32_e32 v0, v1, v0
	v_fma_f32 v0, v1, v0, v1
	v_mul_f32_e32 v0, 0x3fcc422a, v0
	v_mul_f32_e32 v0, 0xbfb8aa3b, v0
	v_exp_f32_e32 v0, v0
	v_mul_f32_e32 v1, v20, v1
	v_add_co_u32_e32 v38, vcc, s2, v36
	v_add_f32_e32 v0, 1.0, v0
	v_rcp_f32_e32 v0, v0
	v_addc_co_u32_e32 v39, vcc, 0, v37, vcc
	v_and_b32_e32 v20, 0xffff0000, v21
	v_mul_f32_e32 v0, v1, v0
	v_cvt_pk_bf16_f32 v0, v0, v49
	global_store_short v[36:37], v0, off offset:2048
	v_mul_f32_e32 v0, 0x3d372713, v2
	v_mul_f32_e32 v0, v2, v0
	v_fma_f32 v0, v2, v0, v2
	v_mul_f32_e32 v0, 0x3fcc422a, v0
	v_mul_f32_e32 v0, 0xbfb8aa3b, v0
	v_exp_f32_e32 v0, v0
	v_lshlrev_b32_e32 v1, 16, v21
	v_add_f32_e32 v1, v142, v1
	v_mul_f32_e32 v1, v1, v2
	v_add_f32_e32 v0, 1.0, v0
	v_rcp_f32_e32 v0, v0
	v_add_f32_e32 v20, v143, v20
	s_movk_i32 s2, 0x3000
	v_mul_f32_e32 v0, v1, v0
	v_cvt_pk_bf16_f32 v2, v0, v49
	v_add_co_u32_e32 v0, vcc, s76, v36
	s_nop 1
	v_addc_co_u32_e32 v1, vcc, 0, v37, vcc
	global_store_short v[0:1], v2, off offset:-4096
	v_mul_f32_e32 v2, 0x3d372713, v3
	v_mul_f32_e32 v2, v3, v2
	v_fma_f32 v2, v3, v2, v3
	v_mul_f32_e32 v2, 0x3fcc422a, v2
	v_mul_f32_e32 v2, 0xbfb8aa3b, v2
	v_exp_f32_e32 v2, v2
	v_mul_f32_e32 v3, v20, v3
	v_add_f32_e32 v2, 1.0, v2
	v_rcp_f32_e32 v2, v2
	s_nop 0
	v_mul_f32_e32 v2, v3, v2
	v_cvt_pk_bf16_f32 v2, v2, v49
	global_store_short v[38:39], v2, off offset:2048
	v_mul_f32_e32 v2, 0x3d372713, v4
	v_mul_f32_e32 v2, v4, v2
	v_fma_f32 v2, v4, v2, v4
	v_mul_f32_e32 v2, 0x3fcc422a, v2
	v_mul_f32_e32 v2, 0xbfb8aa3b, v2
	v_exp_f32_e32 v2, v2
	v_lshlrev_b32_e32 v3, 16, v22
	v_add_f32_e32 v3, v34, v3
	v_mul_f32_e32 v3, v3, v4
	v_add_f32_e32 v2, 1.0, v2
	v_rcp_f32_e32 v2, v2
	s_nop 0
	v_mul_f32_e32 v2, v3, v2
	v_cvt_pk_bf16_f32 v2, v2, v49
	global_store_short v[0:1], v2, off
	v_mul_f32_e32 v2, 0x3d372713, v5
	v_mul_f32_e32 v2, v5, v2
	v_fma_f32 v2, v5, v2, v5
	v_mul_f32_e32 v2, 0x3fcc422a, v2
	v_mul_f32_e32 v2, 0xbfb8aa3b, v2
	v_exp_f32_e32 v2, v2
	v_and_b32_e32 v3, 0xffff0000, v22
	v_add_f32_e32 v3, v35, v3
	v_mul_f32_e32 v3, v3, v5
	v_add_f32_e32 v2, 1.0, v2
	v_rcp_f32_e32 v2, v2
	v_and_b32_e32 v5, 0xffff0000, v23
	v_add_f32_e32 v5, v33, v5
	v_mul_f32_e32 v5, v5, v7
	v_mul_f32_e32 v2, v3, v2
	v_cvt_pk_bf16_f32 v2, v2, v49
	global_store_short v[0:1], v2, off offset:2048
	v_mul_f32_e32 v0, 0x3d372713, v6
	v_mul_f32_e32 v0, v6, v0
	v_fma_f32 v0, v6, v0, v6
	v_mul_f32_e32 v0, 0x3fcc422a, v0
	v_mul_f32_e32 v0, 0xbfb8aa3b, v0
	v_exp_f32_e32 v0, v0
; __device__ __forceinline__ unsigned f2bf(float f) { return pk2(f, 0.0f) & 0xffffu; }
; __device__ __forceinline__ float bflo(unsigned w) { return __uint_as_float(w << 16); }
; __device__ __forceinline__ float bfhi(unsigned w) { return __uint_as_float(w & 0xffff0000u); }
; __device__ __forceinline__ float sigmoidf_(float x) { return __builtin_amdgcn_rcpf(1.0f + __builtin_amdgcn_exp2f(x * -1.4426950408889634f)); }
; template <int DIR>
; __device__ __forceinline__ void lru_dir(const bf16_t* XR, const bf16_t* GATE, bf16_t* YP, u32x4* HSF, const bf16_t* bdw_dir, float bias_r, float bias_i, float sp,
;                                         int b, int n2, int lane, int wave, LAS float* xl) {
;     ...
;                     bf16_t* yp = YP + (size_t)(trow[k] + 16 * hh) * DM + chcol + e;
; #pragma unroll
;                     for (int r = 0; r < 16; ++r) { const float x = gv[r], u2 = 1.5957691216f * (x + 0.044715f * x * x * x);
;                         const float hf = (r & 1) ? bfhi(hw[r >> 1]) : bflo(hw[r >> 1]);
;                         const float y = (hf + hs[r]) * x * sigmoidf_(u2);
;                         yp[(size_t)r * DM] = (bf16_t)f2bf(y); }
	v_lshlrev_b32_e32 v1, 16, v23
	v_add_f32_e32 v1, v32, v1
	v_mul_f32_e32 v1, v1, v6
	v_add_f32_e32 v0, 1.0, v0
	v_rcp_f32_e32 v0, v0
	s_nop 0
	v_mul_f32_e32 v0, v1, v0
	v_cvt_pk_bf16_f32 v4, v0, v49
	v_add_co_u32_e32 v0, vcc, s2, v36
	s_movk_i32 s2, 0x4000
	s_nop 0
	v_addc_co_u32_e32 v1, vcc, 0, v37, vcc
	v_add_co_u32_e32 v2, vcc, s2, v36
	s_movk_i32 s2, 0x5000
	s_nop 0
	v_addc_co_u32_e32 v3, vcc, 0, v37, vcc
	global_store_short v[2:3], v4, off offset:-4096
	v_mul_f32_e32 v4, 0x3d372713, v7
	v_mul_f32_e32 v4, v7, v4
	v_fma_f32 v4, v7, v4, v7
	v_mul_f32_e32 v4, 0x3fcc422a, v4
	v_mul_f32_e32 v4, 0xbfb8aa3b, v4
	v_exp_f32_e32 v4, v4
	s_nop 0
	v_add_f32_e32 v4, 1.0, v4
	v_rcp_f32_e32 v4, v4
	s_nop 0
	v_mul_f32_e32 v4, v5, v4
	v_cvt_pk_bf16_f32 v4, v4, v49
	global_store_short v[0:1], v4, off offset:2048
	v_mul_f32_e32 v0, 0x3d372713, v8
	v_mul_f32_e32 v0, v8, v0
	v_fma_f32 v0, v8, v0, v8
	v_mul_f32_e32 v0, 0x3fcc422a, v0
	v_mul_f32_e32 v0, 0xbfb8aa3b, v0
	v_exp_f32_e32 v0, v0
	v_lshlrev_b32_e32 v1, 16, v16
	v_add_f32_e32 v1, v24, v1
	v_mul_f32_e32 v1, v1, v8
	v_add_f32_e32 v0, 1.0, v0
	v_rcp_f32_e32 v0, v0
	v_and_b32_e32 v5, 0xffff0000, v17
	v_add_f32_e32 v5, v27, v5
	v_mul_f32_e32 v5, v5, v11
	v_mul_f32_e32 v0, v1, v0
	v_cvt_pk_bf16_f32 v0, v0, v49
	global_store_short v[2:3], v0, off
	v_mul_f32_e32 v0, 0x3d372713, v9
	v_mul_f32_e32 v0, v9, v0
	v_fma_f32 v0, v9, v0, v9
	v_mul_f32_e32 v0, 0x3fcc422a, v0
	v_mul_f32_e32 v0, 0xbfb8aa3b, v0
	v_exp_f32_e32 v0, v0
	v_and_b32_e32 v1, 0xffff0000, v16
	v_add_f32_e32 v1, v25, v1
	v_mul_f32_e32 v1, v1, v9
	v_add_f32_e32 v0, 1.0, v0
	v_rcp_f32_e32 v0, v0
	s_nop 0
	v_mul_f32_e32 v0, v1, v0
	v_cvt_pk_bf16_f32 v0, v0, v49
	global_store_short v[2:3], v0, off offset:2048
	v_mul_f32_e32 v0, 0x3d372713, v10
	v_mul_f32_e32 v0, v10, v0
	v_fma_f32 v0, v10, v0, v10
	v_mul_f32_e32 v0, 0x3fcc422a, v0
	v_mul_f32_e32 v0, 0xbfb8aa3b, v0
	v_exp_f32_e32 v0, v0
	v_lshlrev_b32_e32 v1, 16, v17
	v_add_f32_e32 v1, v26, v1
	v_mul_f32_e32 v1, v1, v10
	v_add_f32_e32 v0, 1.0, v0
	v_rcp_f32_e32 v0, v0
	s_nop 0
	v_mul_f32_e32 v0, v1, v0
	v_cvt_pk_bf16_f32 v4, v0, v49
	v_add_co_u32_e32 v0, vcc, s2, v36
	s_movk_i32 s2, 0x7000
	s_nop 0
	v_addc_co_u32_e32 v1, vcc, 0, v37, vcc
	v_add_co_u32_e32 v2, vcc, s4, v36
	s_nop 1
	v_addc_co_u32_e32 v3, vcc, 0, v37, vcc
	global_store_short v[2:3], v4, off offset:-4096
	v_mul_f32_e32 v4, 0x3d372713, v11
	v_mul_f32_e32 v4, v11, v4
	v_fma_f32 v4, v11, v4, v11
	v_mul_f32_e32 v4, 0x3fcc422a, v4
	v_mul_f32_e32 v4, 0xbfb8aa3b, v4
	v_exp_f32_e32 v4, v4
	s_nop 0
	v_add_f32_e32 v4, 1.0, v4
	v_rcp_f32_e32 v4, v4
	s_nop 0
	v_mul_f32_e32 v4, v5, v4
	v_cvt_pk_bf16_f32 v4, v4, v49
	global_store_short v[0:1], v4, off offset:2048
	v_mul_f32_e32 v0, 0x3d372713, v12
	v_mul_f32_e32 v0, v12, v0
	v_fma_f32 v0, v12, v0, v12
	v_mul_f32_e32 v0, 0x3fcc422a, v0
	v_mul_f32_e32 v0, 0xbfb8aa3b, v0
	v_exp_f32_e32 v0, v0
	v_lshlrev_b32_e32 v1, 16, v18
	v_add_f32_e32 v1, v28, v1
	v_mul_f32_e32 v1, v1, v12
	v_add_f32_e32 v0, 1.0, v0
	v_rcp_f32_e32 v0, v0
	s_nop 0
	v_mul_f32_e32 v0, v1, v0
	v_cvt_pk_bf16_f32 v0, v0, v49
	global_store_short v[2:3], v0, off
	v_mul_f32_e32 v0, 0x3d372713, v13
	v_mul_f32_e32 v0, v13, v0
	v_fma_f32 v0, v13, v0, v13
	v_mul_f32_e32 v0, 0x3fcc422a, v0
	v_mul_f32_e32 v0, 0xbfb8aa3b, v0
	v_exp_f32_e32 v0, v0
	v_and_b32_e32 v1, 0xffff0000, v18
	v_add_f32_e32 v1, v29, v1
	v_mul_f32_e32 v1, v1, v13
	v_add_f32_e32 v0, 1.0, v0
	v_rcp_f32_e32 v0, v0
	s_nop 0
	v_mul_f32_e32 v0, v1, v0
	v_cvt_pk_bf16_f32 v0, v0, v49
	global_store_short v[2:3], v0, off offset:2048
	v_mul_f32_e32 v0, 0x3d372713, v14
	v_mul_f32_e32 v0, v14, v0
	v_fma_f32 v0, v14, v0, v14
	v_mul_f32_e32 v0, 0x3fcc422a, v0
	v_mul_f32_e32 v0, 0xbfb8aa3b, v0
	v_exp_f32_e32 v0, v0
	v_lshlrev_b32_e32 v1, 16, v19
	v_add_f32_e32 v1, v30, v1
	v_mul_f32_e32 v1, v1, v14
	v_add_f32_e32 v0, 1.0, v0
	v_rcp_f32_e32 v0, v0
	v_and_b32_e32 v3, 0xffff0000, v19
	v_add_f32_e32 v3, v31, v3
	v_mul_f32_e32 v3, v3, v15
	v_mul_f32_e32 v0, v1, v0
	v_cvt_pk_bf16_f32 v2, v0, v49
	v_add_co_u32_e32 v0, vcc, s2, v36
	s_nop 1
	v_addc_co_u32_e32 v1, vcc, 0, v37, vcc
	global_store_short v[0:1], v2, off
	v_mul_f32_e32 v2, 0x3d372713, v15
	v_mul_f32_e32 v2, v15, v2
	v_fma_f32 v2, v15, v2, v15
	v_mul_f32_e32 v2, 0x3fcc422a, v2
	v_mul_f32_e32 v2, 0xbfb8aa3b, v2
	v_exp_f32_e32 v2, v2
	s_nop 0
	v_add_f32_e32 v2, 1.0, v2
	v_rcp_f32_e32 v2, v2
	s_nop 0
	v_mul_f32_e32 v2, v3, v2
	v_cvt_pk_bf16_f32 v2, v2, v49
	global_store_short v[0:1], v2, off offset:2048

; template <int DIR>
; __device__ __forceinline__ void lru_dir(const bf16_t* XR, const bf16_t* GATE, bf16_t* YP, u32x4* HSF, const bf16_t* bdw_dir, float bias_r, float bias_i, float sp,
;                                         int b, int n2, int lane, int wave, LAS float* xl) {
;     ...
;         for (int k = 0; k < 2; ++k) {
;             const int q = seg * 16 + wave * 2 + k; valid[k] = q < 136;
;             const int T = DIR == 0 ? q : (q < 8 ? 7 - q : 143 - q);
;             trow[k] = T < 8 ? ML + b * CTXL + 32 * T : b * SEQ + 32 * (T - 8);
;             if (valid[k]) {
;                 const bf16_t* ap = XR + (size_t)(trow[k] + tau) * DM + n * 64 + 8 * hh;
;                 bf16x8 A[4];
; #pragma unroll
;                 for (int kk = 0; kk < 4; ++kk) A[kk] = *(const bf16x8*)(ap + 16 * kk);
;                 f32x16 ar, ai, xv;
; #pragma unroll
;                 for (int r = 0; r < 16; ++r) { ar[r] = 0.f; ai[r] = 0.f; xv[r] = 0.f; }
; #pragma unroll
;                 for (int kk = 0; kk < 4; ++kk) { ar = mfma32(A[kk], Br[kk], ar); ai = mfma32(A[kk], Bi[kk], ai); }
;                 const bf16x8 Ax0 = half ? A[2] : A[0], Ax1 = half ? A[3] : A[1];
;                 xv = mfma32(Ax0, I0, xv); xv = mfma32(Ax1, I1, xv);
;                 typedef float f32x2 __attribute__((ext_vector_type(2)));
; #pragma unroll
;                 for (int r = 0; r < 16; r += 2) {
;                     const f32x2 er = ((f32x2){ar[r], ar[r + 1]} + bias_r) * -1.4426950408889634f, ei = ((f32x2){ai[r], ai[r + 1]} + bias_i) * -1.4426950408889634f;
;                     const f32x2 dr = (f32x2){__builtin_amdgcn_exp2f(er[0]), __builtin_amdgcn_exp2f(er[1])} + 1.0f, di = (f32x2){__builtin_amdgcn_exp2f(ei[0]), __builtin_amdgcn_exp2f(ei[1])} + 1.0f;
;                     const f32x2 rg = {__builtin_amdgcn_rcpf(dr[0]), __builtin_amdgcn_rcpf(dr[1])}, ig = {__builtin_amdgcn_rcpf(di[0]), __builtin_amdgcn_rcpf(di[1])};
;                     const f32x2 la = rg * spm;
;                     const f32x2 aa = {__builtin_amdgcn_exp2f(la[0]), __builtin_amdgcn_exp2f(la[1])};
;                     const f32x2 om = __builtin_elementwise_max(1.0f - aa * aa, (f32x2){0.f, 0.f});
;                     const f32x2 bb = (f32x2){__builtin_amdgcn_sqrtf(om[0]), __builtin_amdgcn_sqrtf(om[1])} * ig * (f32x2){xv[r], xv[r + 1]};
.LBB0_48:
	s_cmpk_lt_i32 s35, 0x88
	s_cselect_b64 s[8:9], -1, 0
	s_cmp_gt_i32 s35, 7
	s_cselect_b32 s2, 0x8f, 7
	s_add_i32 s2, s2, s19
	s_lshl_b32 s3, s2, 5
	s_cmp_lt_i32 s2, 8
	s_cselect_b32 s36, s31, s29
	s_add_i32 s36, s36, s3
	v_or_b32_e32 v132, s36, v173
	s_cmpk_gt_i32 s35, 0x87
	v_mov_b32_e32 v126, 1.0
	v_ashrrev_i32_e32 v133, 31, v132
	v_mov_b32_e32 v138, 0
	v_mov_b32_e32 v139, 0
	v_mov_b32_e32 v134, 0
	v_mov_b32_e32 v135, 0
	v_mov_b32_e32 v136, 0
	v_mov_b32_e32 v137, 0
	v_mov_b32_e32 v128, 0
	v_mov_b32_e32 v129, 0
	v_mov_b32_e32 v130, 0
	v_mov_b32_e32 v131, 0
	v_mov_b32_e32 v146, 0
	v_mov_b32_e32 v147, 0
	v_mov_b32_e32 v148, 0
	v_mov_b32_e32 v149, 0
	v_mov_b32_e32 v150, 0
	v_mov_b32_e32 v151, 0
	v_mov_b32_e32 v140, 1.0
	v_mov_b32_e32 v141, 1.0
	v_mov_b32_e32 v152, 1.0
	v_mov_b32_e32 v153, 1.0
	v_mov_b32_e32 v156, 1.0
	v_mov_b32_e32 v157, 1.0
	v_mov_b32_e32 v158, 1.0
	v_mov_b32_e32 v159, 1.0
	v_mov_b32_e32 v162, 1.0
	v_mov_b32_e32 v163, 1.0
	v_mov_b32_e32 v164, 1.0
	v_mov_b32_e32 v165, 1.0
	v_mov_b32_e32 v166, 1.0
	v_mov_b32_e32 v167, 1.0
	v_mov_b32_e32 v168, 1.0
	v_mov_b32_e32 v169, 1.0
	s_cbranch_scc1 .LBB0_50
	v_lshlrev_b64 v[0:1], 11, v[132:133]
	v_lshl_add_u64 v[12:13], v[118:119], 0, v[0:1]
	global_load_dwordx4 v[0:3], v[12:13], off
	global_load_dwordx4 v[4:7], v[12:13], off offset:32
	global_load_dwordx4 v[8:11], v[12:13], off offset:64
	s_nop 0
	global_load_dwordx4 v[12:15], v[12:13], off offset:96
	s_ashr_i32 s98, s36, 12
	s_mulk_i32 s98, 0x88
	s_bfe_u32 s99, s36, 0x70005
	s_add_i32 s98, s98, s99
	s_add_i32 s98, s98, 8
	s_sub_i32 s99, s36, s30
	s_addk_i32 s99, 0x8000
	s_ashr_i32 s99, s99, 5
	s_add_i32 s99, s99, s34
	s_cmp_lt_i32 s36, 0x8000
	s_cselect_b32 s98, s98, s99
	s_ashr_i32 s99, s98, 31
	s_lshl_b64 s[98:99], s[98:99], 16
	v_lshl_add_u64 v[216:217], v[112:113], 0, s[98:99]
	v_lshlrev_b64 v[218:219], 11, v[132:133]
	global_load_dwordx4 v[184:187], v[216:217], off offset:16
	global_load_dwordx4 v[188:191], v[216:217], off
	v_lshl_add_u64 v[218:219], v[120:121], 0, v[218:219]
	s_nop 0
	global_load_dwordx4 v[192:195], v[218:219], off
	global_load_dwordx4 v[196:199], v[218:219], off offset:32
	s_waitcnt vmcnt(7)
	v_mfma_f32_32x32x16_bf16 v[32:47], v[0:3], v[66:69], 0
	s_waitcnt vmcnt(4)
	v_cndmask_b32_e64 v131, v15, v7, s[56:57]
	v_cndmask_b32_e64 v130, v14, v6, s[56:57]
	v_cndmask_b32_e64 v129, v13, v5, s[56:57]
	v_cndmask_b32_e64 v128, v12, v4, s[56:57]
	v_mfma_f32_32x32x16_bf16 v[32:47], v[4:7], v[70:73], v[32:47]
	v_mfma_f32_32x32x16_bf16 v[16:31], v[0:3], v[82:85], 0
	v_cndmask_b32_e64 v3, v11, v3, s[56:57]
	v_cndmask_b32_e64 v2, v10, v2, s[56:57]
	v_cndmask_b32_e64 v1, v9, v1, s[56:57]
	v_cndmask_b32_e64 v0, v8, v0, s[56:57]
	v_mfma_f32_32x32x16_bf16 v[32:47], v[8:11], v[74:77], v[32:47]
	v_mfma_f32_32x32x16_bf16 v[16:31], v[4:7], v[86:89], v[16:31]
	v_mfma_f32_32x32x16_bf16 v[32:47], v[12:15], v[78:81], v[32:47]
	v_mfma_f32_32x32x16_bf16 v[16:31], v[8:11], v[90:93], v[16:31]
	s_nop 10
	v_add_f32_e64 v32, v114, v32
	v_add_f32_e64 v33, v115, v33
	v_mul_f32_e64 v32, v32, s14
	v_mul_f32_e64 v33, v33, s14
	v_exp_f32_e32 v32, v32
	v_exp_f32_e32 v33, v33
	v_mfma_f32_32x32x16_bf16 v[16:31], v[12:15], v[94:97], v[16:31]
	v_add_f32_e64 v32, v32, 1.0
	v_add_f32_e64 v33, v33, 1.0
	v_rcp_f32_e32 v32, v32
	v_rcp_f32_e32 v33, v33
	s_nop 0
	v_pk_mul_f32 v[32:33], v[124:125], v[32:33]
	v_mfma_f32_32x32x16_bf16 v[0:15], v[0:3], v[58:61], 0
	s_nop 4
	v_add_f32_e64 v16, v116, v16
	v_add_f32_e64 v17, v117, v17
	v_exp_f32_e32 v140, v32
	v_pk_mul_f32 v[16:17], v[16:17], s[14:15] op_sel_hi:[1,0]
	v_exp_f32_e32 v141, v33
	v_exp_f32_e32 v16, v16
	v_exp_f32_e32 v17, v17
	v_pk_fma_f32 v[32:33], v[140:141], v[140:141], 1.0 op_sel_hi:[1,1,0] neg_lo:[1,0,0] neg_hi:[1,0,0]
	v_mfma_f32_32x32x16_bf16 v[0:15], v[128:131], v[62:65], v[0:15]
	v_add_f32_e64 v16, v16, 1.0
	v_add_f32_e64 v17, v17, 1.0
	v_max_f32_e32 v33, 0, v33
	v_max_f32_e32 v32, 0, v32
	v_rcp_f32_e32 v16, v16
	v_rcp_f32_e32 v17, v17
	v_sqrt_f32_e32 v32, v32
	v_sqrt_f32_e32 v33, v33
	s_nop 0
	v_pk_mul_f32 v[16:17], v[16:17], v[32:33]
	s_nop 1
	v_pk_mul_f32 v[138:139], v[0:1], v[16:17]
	v_pk_add_f32 v[0:1], v[114:115], v[34:35]
	v_pk_add_f32 v[16:17], v[116:117], v[18:19]
	v_pk_mul_f32 v[0:1], v[0:1], s[14:15] op_sel_hi:[1,0]
	v_pk_mul_f32 v[16:17], v[16:17], s[14:15] op_sel_hi:[1,0]
	v_exp_f32_e32 v0, v0
	v_exp_f32_e32 v1, v1
	v_exp_f32_e32 v16, v16
	v_exp_f32_e32 v17, v17
	v_pk_add_f32 v[0:1], v[0:1], 1.0 op_sel_hi:[1,0]
	s_nop 0
	v_rcp_f32_e32 v0, v0
	v_rcp_f32_e32 v1, v1
	v_pk_add_f32 v[16:17], v[16:17], 1.0 op_sel_hi:[1,0]
	v_pk_mul_f32 v[0:1], v[124:125], v[0:1]
	s_nop 0
	v_exp_f32_e32 v152, v0
	v_exp_f32_e32 v153, v1
	v_rcp_f32_e32 v16, v16
	v_rcp_f32_e32 v17, v17
	v_pk_fma_f32 v[0:1], v[152:153], v[152:153], 1.0 op_sel_hi:[1,1,0] neg_lo:[1,0,0] neg_hi:[1,0,0]
	s_nop 0
	v_max_f32_e32 v1, 0, v1
	v_max_f32_e32 v0, 0, v0
	v_sqrt_f32_e32 v0, v0
	v_sqrt_f32_e32 v1, v1
	s_nop 0
	v_pk_mul_f32 v[0:1], v[16:17], v[0:1]
	s_nop 0
	v_pk_mul_f32 v[134:135], v[2:3], v[0:1]
	v_pk_add_f32 v[0:1], v[114:115], v[36:37]
	v_pk_add_f32 v[2:3], v[116:117], v[20:21]
	v_pk_mul_f32 v[0:1], v[0:1], s[14:15] op_sel_hi:[1,0]
	v_pk_mul_f32 v[2:3], v[2:3], s[14:15] op_sel_hi:[1,0]
	v_exp_f32_e32 v0, v0
	v_exp_f32_e32 v1, v1
	v_exp_f32_e32 v2, v2
	v_exp_f32_e32 v3, v3
	v_pk_add_f32 v[0:1], v[0:1], 1.0 op_sel_hi:[1,0]
	s_nop 0
	v_rcp_f32_e32 v0, v0
	v_rcp_f32_e32 v1, v1
	v_pk_add_f32 v[2:3], v[2:3], 1.0 op_sel_hi:[1,0]
	v_pk_mul_f32 v[0:1], v[124:125], v[0:1]
	s_nop 0
	v_exp_f32_e32 v156, v0
	v_exp_f32_e32 v157, v1
	v_rcp_f32_e32 v2, v2
	v_rcp_f32_e32 v3, v3
	v_pk_fma_f32 v[0:1], v[156:157], v[156:157], 1.0 op_sel_hi:[1,1,0] neg_lo:[1,0,0] neg_hi:[1,0,0]
; template <int DIR>
; __device__ __forceinline__ void lru_dir(const bf16_t* XR, const bf16_t* GATE, bf16_t* YP, u32x4* HSF, const bf16_t* bdw_dir, float bias_r, float bias_i, float sp,
;                                         int b, int n2, int lane, int wave, LAS float* xl) {
;     ...
; #pragma unroll
;                 for (int r = 0; r < 16; r += 2) {
;                     const f32x2 er = ((f32x2){ar[r], ar[r + 1]} + bias_r) * -1.4426950408889634f, ei = ((f32x2){ai[r], ai[r + 1]} + bias_i) * -1.4426950408889634f;
;                     const f32x2 dr = (f32x2){__builtin_amdgcn_exp2f(er[0]), __builtin_amdgcn_exp2f(er[1])} + 1.0f, di = (f32x2){__builtin_amdgcn_exp2f(ei[0]), __builtin_amdgcn_exp2f(ei[1])} + 1.0f;
;                     const f32x2 rg = {__builtin_amdgcn_rcpf(dr[0]), __builtin_amdgcn_rcpf(dr[1])}, ig = {__builtin_amdgcn_rcpf(di[0]), __builtin_amdgcn_rcpf(di[1])};
;                     const f32x2 la = rg * spm;
;                     const f32x2 aa = {__builtin_amdgcn_exp2f(la[0]), __builtin_amdgcn_exp2f(la[1])};
;                     const f32x2 om = __builtin_elementwise_max(1.0f - aa * aa, (f32x2){0.f, 0.f});
;                     const f32x2 bb = (f32x2){__builtin_amdgcn_sqrtf(om[0]), __builtin_amdgcn_sqrtf(om[1])} * ig * (f32x2){xv[r], xv[r + 1]};
;                     av[k][r] = aa[0]; av[k][r + 1] = aa[1]; bv[k][r] = bb[0]; bv[k][r + 1] = bb[1];
;                 }
	s_nop 0
	v_max_f32_e32 v1, 0, v1
	v_max_f32_e32 v0, 0, v0
	v_sqrt_f32_e32 v0, v0
	v_sqrt_f32_e32 v1, v1
	s_nop 0
	v_pk_mul_f32 v[0:1], v[2:3], v[0:1]
	s_nop 0
	v_pk_mul_f32 v[136:137], v[4:5], v[0:1]
	v_pk_add_f32 v[0:1], v[114:115], v[38:39]
	v_pk_add_f32 v[2:3], v[116:117], v[22:23]
	v_pk_mul_f32 v[0:1], v[0:1], s[14:15] op_sel_hi:[1,0]
	v_pk_mul_f32 v[2:3], v[2:3], s[14:15] op_sel_hi:[1,0]
	v_exp_f32_e32 v0, v0
	v_exp_f32_e32 v1, v1
	v_exp_f32_e32 v2, v2
	v_exp_f32_e32 v3, v3
	v_pk_add_f32 v[0:1], v[0:1], 1.0 op_sel_hi:[1,0]
	s_nop 0
	v_rcp_f32_e32 v0, v0
	v_rcp_f32_e32 v1, v1
	v_pk_add_f32 v[2:3], v[2:3], 1.0 op_sel_hi:[1,0]
	v_pk_mul_f32 v[0:1], v[124:125], v[0:1]
	s_nop 0
	v_exp_f32_e32 v158, v0
	v_exp_f32_e32 v159, v1
	v_rcp_f32_e32 v2, v2
	v_rcp_f32_e32 v3, v3
	v_pk_fma_f32 v[0:1], v[158:159], v[158:159], 1.0 op_sel_hi:[1,1,0] neg_lo:[1,0,0] neg_hi:[1,0,0]
	s_nop 0
	v_max_f32_e32 v1, 0, v1
	v_max_f32_e32 v0, 0, v0
	v_sqrt_f32_e32 v0, v0
	v_sqrt_f32_e32 v1, v1
	s_nop 0
	v_pk_mul_f32 v[0:1], v[2:3], v[0:1]
	s_nop 0
	v_pk_mul_f32 v[128:129], v[6:7], v[0:1]
	v_pk_add_f32 v[0:1], v[114:115], v[40:41]
	v_pk_add_f32 v[2:3], v[116:117], v[24:25]
	v_pk_mul_f32 v[0:1], v[0:1], s[14:15] op_sel_hi:[1,0]
	v_pk_mul_f32 v[2:3], v[2:3], s[14:15] op_sel_hi:[1,0]
	v_exp_f32_e32 v0, v0
	v_exp_f32_e32 v1, v1
	v_exp_f32_e32 v2, v2
	v_exp_f32_e32 v3, v3
	v_pk_add_f32 v[0:1], v[0:1], 1.0 op_sel_hi:[1,0]
	s_nop 0
	v_rcp_f32_e32 v0, v0
	v_rcp_f32_e32 v1, v1
	v_pk_add_f32 v[2:3], v[2:3], 1.0 op_sel_hi:[1,0]
	v_pk_mul_f32 v[0:1], v[124:125], v[0:1]
	s_nop 0
	v_exp_f32_e32 v162, v0
	v_exp_f32_e32 v163, v1
	v_rcp_f32_e32 v2, v2
	v_rcp_f32_e32 v3, v3
	v_pk_fma_f32 v[0:1], v[162:163], v[162:163], 1.0 op_sel_hi:[1,1,0] neg_lo:[1,0,0] neg_hi:[1,0,0]
	s_nop 0
	v_max_f32_e32 v1, 0, v1
	v_max_f32_e32 v0, 0, v0
	v_sqrt_f32_e32 v0, v0
	v_sqrt_f32_e32 v1, v1
	s_nop 0
	v_pk_mul_f32 v[0:1], v[2:3], v[0:1]
	s_nop 0
	v_pk_mul_f32 v[130:131], v[8:9], v[0:1]
	v_pk_add_f32 v[0:1], v[114:115], v[42:43]
	v_pk_add_f32 v[2:3], v[116:117], v[26:27]
	v_pk_mul_f32 v[0:1], v[0:1], s[14:15] op_sel_hi:[1,0]
	v_pk_mul_f32 v[2:3], v[2:3], s[14:15] op_sel_hi:[1,0]
	v_exp_f32_e32 v0, v0
	v_exp_f32_e32 v1, v1
	v_exp_f32_e32 v2, v2
	v_exp_f32_e32 v3, v3
	v_pk_add_f32 v[0:1], v[0:1], 1.0 op_sel_hi:[1,0]
	s_nop 0
	v_rcp_f32_e32 v0, v0
	v_rcp_f32_e32 v1, v1
	v_pk_add_f32 v[2:3], v[2:3], 1.0 op_sel_hi:[1,0]
	v_pk_mul_f32 v[0:1], v[124:125], v[0:1]
	s_nop 0
	v_exp_f32_e32 v164, v0
	v_exp_f32_e32 v165, v1
	v_rcp_f32_e32 v2, v2
	v_rcp_f32_e32 v3, v3
	v_pk_fma_f32 v[0:1], v[164:165], v[164:165], 1.0 op_sel_hi:[1,1,0] neg_lo:[1,0,0] neg_hi:[1,0,0]
	s_nop 0
	v_max_f32_e32 v1, 0, v1
	v_max_f32_e32 v0, 0, v0
	v_sqrt_f32_e32 v0, v0
	v_sqrt_f32_e32 v1, v1
	s_nop 0
	v_pk_mul_f32 v[0:1], v[2:3], v[0:1]
	s_nop 0
	v_pk_mul_f32 v[146:147], v[10:11], v[0:1]
	v_pk_add_f32 v[0:1], v[114:115], v[44:45]
	v_pk_add_f32 v[2:3], v[116:117], v[28:29]
	v_pk_mul_f32 v[0:1], v[0:1], s[14:15] op_sel_hi:[1,0]
	v_pk_mul_f32 v[2:3], v[2:3], s[14:15] op_sel_hi:[1,0]
	v_exp_f32_e32 v0, v0
	v_exp_f32_e32 v1, v1
	v_exp_f32_e32 v2, v2
	v_exp_f32_e32 v3, v3
	v_pk_add_f32 v[0:1], v[0:1], 1.0 op_sel_hi:[1,0]
	s_nop 0
	v_rcp_f32_e32 v0, v0
	v_rcp_f32_e32 v1, v1
	v_pk_add_f32 v[2:3], v[2:3], 1.0 op_sel_hi:[1,0]
	v_pk_mul_f32 v[0:1], v[124:125], v[0:1]
	s_nop 0
	v_exp_f32_e32 v166, v0
	v_exp_f32_e32 v167, v1
	v_rcp_f32_e32 v2, v2
	v_rcp_f32_e32 v3, v3
	v_pk_fma_f32 v[0:1], v[166:167], v[166:167], 1.0 op_sel_hi:[1,1,0] neg_lo:[1,0,0] neg_hi:[1,0,0]
	s_nop 0
	v_max_f32_e32 v1, 0, v1
	v_max_f32_e32 v0, 0, v0
	v_sqrt_f32_e32 v0, v0
	v_sqrt_f32_e32 v1, v1
	s_nop 0
	v_pk_mul_f32 v[0:1], v[2:3], v[0:1]
	s_nop 0
	v_pk_mul_f32 v[148:149], v[12:13], v[0:1]
	v_pk_add_f32 v[0:1], v[114:115], v[46:47]
	v_pk_add_f32 v[2:3], v[116:117], v[30:31]
	v_pk_mul_f32 v[0:1], v[0:1], s[14:15] op_sel_hi:[1,0]
	v_pk_mul_f32 v[2:3], v[2:3], s[14:15] op_sel_hi:[1,0]
	v_exp_f32_e32 v0, v0
	v_exp_f32_e32 v1, v1
	v_exp_f32_e32 v2, v2
	v_exp_f32_e32 v3, v3
	v_pk_add_f32 v[0:1], v[0:1], 1.0 op_sel_hi:[1,0]
	s_nop 0
	v_rcp_f32_e32 v0, v0
	v_rcp_f32_e32 v1, v1
	v_pk_add_f32 v[2:3], v[2:3], 1.0 op_sel_hi:[1,0]
	v_pk_mul_f32 v[0:1], v[124:125], v[0:1]
	s_nop 0
	v_exp_f32_e32 v168, v0
	v_exp_f32_e32 v169, v1
	v_rcp_f32_e32 v2, v2
	v_rcp_f32_e32 v3, v3
	v_pk_fma_f32 v[0:1], v[168:169], v[168:169], 1.0 op_sel_hi:[1,1,0] neg_lo:[1,0,0] neg_hi:[1,0,0]
	s_nop 0
	v_max_f32_e32 v1, 0, v1
	v_max_f32_e32 v0, 0, v0
	v_sqrt_f32_e32 v0, v0
	v_sqrt_f32_e32 v1, v1
	s_nop 0
	v_pk_mul_f32 v[0:1], v[2:3], v[0:1]
	s_nop 0
	v_pk_mul_f32 v[150:151], v[14:15], v[0:1]
; __device__ __forceinline__ f32x16 mfma32(bf16x8 a, bf16x8 b, f32x16 c) { return __builtin_amdgcn_mfma_f32_32x32x16_bf16(a, b, c, 0, 0, 0); }
; template <int DIR>
; __device__ __forceinline__ void lru_dir(const bf16_t* XR, const bf16_t* GATE, bf16_t* YP, u32x4* HSF, const bf16_t* bdw_dir, float bias_r, float bias_i, float sp,
;                                         int b, int n2, int lane, int wave, LAS float* xl) {
;     ...
;         for (int k = 0; k < 2; ++k) {
;             const int q = seg * 16 + wave * 2 + k; valid[k] = q < 136;
;             const int T = DIR == 0 ? q : (q < 8 ? 7 - q : 143 - q);
;             trow[k] = T < 8 ? ML + b * CTXL + 32 * T : b * SEQ + 32 * (T - 8);
;             if (valid[k]) {
;                 const bf16_t* ap = XR + (size_t)(trow[k] + tau) * DM + n * 64 + 8 * hh;
;                 bf16x8 A[4];
; #pragma unroll
;                 for (int kk = 0; kk < 4; ++kk) A[kk] = *(const bf16x8*)(ap + 16 * kk);
;                 f32x16 ar, ai, xv;
; #pragma unroll
;                 for (int r = 0; r < 16; ++r) { ar[r] = 0.f; ai[r] = 0.f; xv[r] = 0.f; }
; #pragma unroll
;                 for (int kk = 0; kk < 4; ++kk) { ar = mfma32(A[kk], Br[kk], ar); ai = mfma32(A[kk], Bi[kk], ai); }
;                 const bf16x8 Ax0 = half ? A[2] : A[0], Ax1 = half ? A[3] : A[1];
;                 xv = mfma32(Ax0, I0, xv); xv = mfma32(Ax1, I1, xv);
;     ...
;             float H = 0.f, P = 1.f;
; #pragma unroll
;             for (int rr = 0; rr < 16; ++rr) { const int r = DIR == 0 ? rr : 15 - rr; H = av[k][r] * H + bv[k][r]; P *= av[k][r]; }
;             Hl[k] = H; Pl[k] = P;
;             const float val = H + P * hloc, got = __shfl_xor(val, 32);
;             const float st2 = first ? hloc : got;
;             const float endv = H + P * st2, got2 = __shfl_xor(endv, 32);
;             hloc = first ? got2 : endv;
;             ploc *= P * __shfl_xor(P, 32);
;         }
.LBB0_50:
	s_nop 0
	v_fma_f32 v0, 0, v169, v151
	v_fma_f32 v0, v168, v0, v150
	v_mul_f32_e32 v1, v169, v168
	v_fma_f32 v0, v167, v0, v149
	v_mul_f32_e32 v1, v167, v1
	v_fma_f32 v0, v166, v0, v148
	v_mul_f32_e32 v1, v166, v1
	v_fma_f32 v0, v165, v0, v147
	v_mul_f32_e32 v1, v165, v1
	v_fma_f32 v0, v164, v0, v146
	v_mul_f32_e32 v1, v164, v1
	v_fma_f32 v0, v163, v0, v131
	v_mul_f32_e32 v1, v163, v1
	v_fma_f32 v0, v162, v0, v130
	v_mul_f32_e32 v1, v162, v1
	v_fma_f32 v0, v159, v0, v129
	v_mul_f32_e32 v1, v159, v1
	v_fma_f32 v0, v158, v0, v128
	v_mul_f32_e32 v1, v158, v1
	v_fma_f32 v0, v157, v0, v137
	v_mul_f32_e32 v1, v157, v1
	v_fma_f32 v0, v156, v0, v136
	v_mul_f32_e32 v1, v156, v1
	v_fma_f32 v0, v153, v0, v135
	v_mul_f32_e32 v1, v153, v1
	v_fma_f32 v0, v152, v0, v134
	v_mul_f32_e32 v1, v152, v1
	v_fma_f32 v0, v141, v0, v139
	v_mul_f32_e32 v1, v141, v1
	v_fma_f32 v111, v140, v0, v138
	v_mul_f32_e32 v175, v140, v1
	v_fma_f32 v0, 0, v175, v111
	ds_bpermute_b32 v0, v176, v0
	s_add_i32 s2, s35, 1
	s_cmpk_lt_i32 s2, 0x88
	s_cselect_b64 s[10:11], -1, 0
	s_cmp_lt_i32 s35, 7
	s_cselect_b32 s3, 7, 0x8f
	s_add_i32 s3, s3, s19
	s_waitcnt lgkmcnt(0)
	v_cndmask_b32_e64 v0, 0, v0, s[40:41]
	s_add_i32 s3, s3, -1
	v_fma_f32 v48, v0, v175, v111
	s_lshl_b32 s6, s3, 5
	ds_bpermute_b32 v99, v176, v48
	ds_bpermute_b32 v98, v176, v175
	s_cmp_lt_i32 s3, 8
	s_cselect_b32 s37, s31, s29
	s_add_i32 s37, s37, s6
	v_or_b32_e32 v144, s37, v173
	v_mov_b32_e32 v154, 0
	s_cmpk_gt_i32 s2, 0x87
	v_ashrrev_i32_e32 v145, 31, v144
	v_mov_b32_e32 v155, 0
	v_mov_b32_e32 v142, 0
	v_mov_b32_e32 v143, 0
	v_mov_b32_e32 v34, 0
	v_mov_b32_e32 v35, 0
	v_mov_b32_e32 v32, 0
	v_mov_b32_e32 v33, 0
	v_mov_b32_e32 v24, 0
	v_mov_b32_e32 v25, 0
	v_mov_b32_e32 v26, 0
	v_mov_b32_e32 v27, 0
	v_mov_b32_e32 v28, 0
	v_mov_b32_e32 v29, 0
	v_mov_b32_e32 v30, 0
	v_mov_b32_e32 v31, 0
	v_mov_b32_e32 v127, 1.0
	v_mov_b32_e32 v160, 1.0
	v_mov_b32_e32 v161, 1.0
	v_mov_b32_e32 v36, 1.0
	v_mov_b32_e32 v37, 1.0
	v_mov_b32_e32 v38, 1.0
	v_mov_b32_e32 v39, 1.0
	v_mov_b32_e32 v40, 1.0
	v_mov_b32_e32 v41, 1.0
	v_mov_b32_e32 v42, 1.0
	v_mov_b32_e32 v43, 1.0
	v_mov_b32_e32 v44, 1.0
	v_mov_b32_e32 v45, 1.0
	v_mov_b32_e32 v46, 1.0
	v_mov_b32_e32 v47, 1.0
	s_cbranch_scc1 .LBB0_52
	v_lshlrev_b64 v[0:1], 11, v[144:145]
	v_lshl_add_u64 v[12:13], v[118:119], 0, v[0:1]
	global_load_dwordx4 v[0:3], v[12:13], off
	global_load_dwordx4 v[4:7], v[12:13], off offset:32
	global_load_dwordx4 v[8:11], v[12:13], off offset:64
	s_nop 0
	global_load_dwordx4 v[12:15], v[12:13], off offset:96
	s_ashr_i32 s98, s37, 12
	s_mulk_i32 s98, 0x88
	s_lshr_b32 s99, s37, 5
	s_and_b32 s99, s99, 0x7e
	s_add_i32 s98, s98, s99
	s_add_i32 s98, s98, 8
	s_sub_i32 s99, s37, s30
	s_addk_i32 s99, 0x8000
	s_ashr_i32 s99, s99, 5
	s_add_i32 s99, s99, s34
	s_cmp_lt_i32 s37, 0x8000
	s_cselect_b32 s98, s98, s99
	s_ashr_i32 s99, s98, 31
	s_lshl_b64 s[98:99], s[98:99], 16
	v_lshl_add_u64 v[216:217], v[112:113], 0, s[98:99]
	v_lshlrev_b64 v[218:219], 11, v[144:145]
	global_load_dwordx4 v[200:203], v[216:217], off offset:16
	global_load_dwordx4 v[204:207], v[216:217], off
	v_lshl_add_u64 v[218:219], v[120:121], 0, v[218:219]
	s_nop 0
	global_load_dwordx4 v[208:211], v[218:219], off
	global_load_dwordx4 v[212:215], v[218:219], off offset:32
	s_waitcnt vmcnt(7)
	v_mfma_f32_32x32x16_bf16 v[32:47], v[0:3], v[66:69], 0
	s_waitcnt vmcnt(4)
	v_cndmask_b32_e64 v183, v15, v7, s[56:57]
	v_cndmask_b32_e64 v182, v14, v6, s[56:57]
	v_cndmask_b32_e64 v181, v13, v5, s[56:57]
	v_cndmask_b32_e64 v180, v12, v4, s[56:57]
	v_mfma_f32_32x32x16_bf16 v[32:47], v[4:7], v[70:73], v[32:47]
	v_mfma_f32_32x32x16_bf16 v[16:31], v[0:3], v[82:85], 0
	v_cndmask_b32_e64 v3, v11, v3, s[56:57]
	v_cndmask_b32_e64 v2, v10, v2, s[56:57]
	v_cndmask_b32_e64 v1, v9, v1, s[56:57]
	v_cndmask_b32_e64 v0, v8, v0, s[56:57]
	v_mfma_f32_32x32x16_bf16 v[32:47], v[8:11], v[74:77], v[32:47]
	v_mfma_f32_32x32x16_bf16 v[16:31], v[4:7], v[86:89], v[16:31]
	v_mfma_f32_32x32x16_bf16 v[32:47], v[12:15], v[78:81], v[32:47]
	v_mfma_f32_32x32x16_bf16 v[16:31], v[8:11], v[90:93], v[16:31]
	s_nop 10
	v_add_f32_e64 v32, v114, v32
	v_add_f32_e64 v33, v115, v33
	v_mul_f32_e64 v32, v32, s14
	v_mul_f32_e64 v33, v33, s14
	v_exp_f32_e32 v32, v32
	v_exp_f32_e32 v33, v33
	v_mfma_f32_32x32x16_bf16 v[16:31], v[12:15], v[94:97], v[16:31]
	v_add_f32_e64 v32, v32, 1.0
	v_add_f32_e64 v33, v33, 1.0
	v_rcp_f32_e32 v32, v32
	v_rcp_f32_e32 v33, v33
	s_nop 0
	v_pk_mul_f32 v[32:33], v[124:125], v[32:33]
	v_mfma_f32_32x32x16_bf16 v[0:15], v[0:3], v[58:61], 0
	s_nop 4
	v_add_f32_e64 v16, v116, v16
	v_add_f32_e64 v17, v117, v17
	v_exp_f32_e32 v126, v32
	v_pk_mul_f32 v[16:17], v[16:17], s[14:15] op_sel_hi:[1,0]
	v_exp_f32_e32 v127, v33
	v_exp_f32_e32 v16, v16
	v_exp_f32_e32 v17, v17
	v_pk_fma_f32 v[32:33], v[126:127], v[126:127], 1.0 op_sel_hi:[1,1,0] neg_lo:[1,0,0] neg_hi:[1,0,0]
	v_mfma_f32_32x32x16_bf16 v[0:15], v[180:183], v[62:65], v[0:15]
	v_add_f32_e64 v16, v16, 1.0
	v_add_f32_e64 v17, v17, 1.0
	v_max_f32_e32 v33, 0, v33
	v_max_f32_e32 v32, 0, v32
	v_rcp_f32_e32 v16, v16
	v_rcp_f32_e32 v17, v17
	v_sqrt_f32_e32 v32, v32
	v_sqrt_f32_e32 v33, v33
	s_nop 0
	v_pk_mul_f32 v[16:17], v[16:17], v[32:33]
	s_nop 1
	v_pk_mul_f32 v[154:155], v[0:1], v[16:17]
	v_pk_add_f32 v[0:1], v[114:115], v[34:35]
	v_pk_add_f32 v[16:17], v[116:117], v[18:19]
	v_pk_mul_f32 v[0:1], v[0:1], s[14:15] op_sel_hi:[1,0]
	v_pk_mul_f32 v[16:17], v[16:17], s[14:15] op_sel_hi:[1,0]
	v_exp_f32_e32 v0, v0
	v_exp_f32_e32 v1, v1
	v_exp_f32_e32 v16, v16
	v_exp_f32_e32 v17, v17
	v_pk_add_f32 v[0:1], v[0:1], 1.0 op_sel_hi:[1,0]
	s_nop 0
	v_rcp_f32_e32 v0, v0
	v_rcp_f32_e32 v1, v1
; template <int DIR>
; __device__ __forceinline__ void lru_dir(const bf16_t* XR, const bf16_t* GATE, bf16_t* YP, u32x4* HSF, const bf16_t* bdw_dir, float bias_r, float bias_i, float sp,
;                                         int b, int n2, int lane, int wave, LAS float* xl) {
;     ...
; #pragma unroll
;                 for (int r = 0; r < 16; r += 2) {
;                     const f32x2 er = ((f32x2){ar[r], ar[r + 1]} + bias_r) * -1.4426950408889634f, ei = ((f32x2){ai[r], ai[r + 1]} + bias_i) * -1.4426950408889634f;
;                     const f32x2 dr = (f32x2){__builtin_amdgcn_exp2f(er[0]), __builtin_amdgcn_exp2f(er[1])} + 1.0f, di = (f32x2){__builtin_amdgcn_exp2f(ei[0]), __builtin_amdgcn_exp2f(ei[1])} + 1.0f;
;                     const f32x2 rg = {__builtin_amdgcn_rcpf(dr[0]), __builtin_amdgcn_rcpf(dr[1])}, ig = {__builtin_amdgcn_rcpf(di[0]), __builtin_amdgcn_rcpf(di[1])};
;                     const f32x2 la = rg * spm;
;                     const f32x2 aa = {__builtin_amdgcn_exp2f(la[0]), __builtin_amdgcn_exp2f(la[1])};
;                     const f32x2 om = __builtin_elementwise_max(1.0f - aa * aa, (f32x2){0.f, 0.f});
;                     const f32x2 bb = (f32x2){__builtin_amdgcn_sqrtf(om[0]), __builtin_amdgcn_sqrtf(om[1])} * ig * (f32x2){xv[r], xv[r + 1]};
;                     av[k][r] = aa[0]; av[k][r + 1] = aa[1]; bv[k][r] = bb[0]; bv[k][r + 1] = bb[1];
;                 }
	v_pk_add_f32 v[16:17], v[16:17], 1.0 op_sel_hi:[1,0]
	v_pk_mul_f32 v[0:1], v[124:125], v[0:1]
	s_nop 0
	v_exp_f32_e32 v160, v0
	v_exp_f32_e32 v161, v1
	v_rcp_f32_e32 v16, v16
	v_rcp_f32_e32 v17, v17
	v_pk_fma_f32 v[0:1], v[160:161], v[160:161], 1.0 op_sel_hi:[1,1,0] neg_lo:[1,0,0] neg_hi:[1,0,0]
	s_nop 0
	v_max_f32_e32 v1, 0, v1
	v_max_f32_e32 v0, 0, v0
	v_sqrt_f32_e32 v0, v0
	v_sqrt_f32_e32 v1, v1
	s_nop 0
	v_pk_mul_f32 v[0:1], v[16:17], v[0:1]
	s_nop 0
	v_pk_mul_f32 v[142:143], v[2:3], v[0:1]
	v_pk_add_f32 v[0:1], v[114:115], v[36:37]
	v_pk_add_f32 v[2:3], v[116:117], v[20:21]
	v_pk_mul_f32 v[0:1], v[0:1], s[14:15] op_sel_hi:[1,0]
	v_pk_mul_f32 v[2:3], v[2:3], s[14:15] op_sel_hi:[1,0]
	v_exp_f32_e32 v0, v0
	v_exp_f32_e32 v1, v1
	v_exp_f32_e32 v2, v2
	v_exp_f32_e32 v3, v3
	v_pk_add_f32 v[0:1], v[0:1], 1.0 op_sel_hi:[1,0]
	s_nop 0
	v_rcp_f32_e32 v0, v0
	v_rcp_f32_e32 v1, v1
	v_pk_add_f32 v[2:3], v[2:3], 1.0 op_sel_hi:[1,0]
	v_pk_mul_f32 v[0:1], v[124:125], v[0:1]
	s_nop 0
	v_exp_f32_e32 v36, v0
	v_exp_f32_e32 v37, v1
	v_rcp_f32_e32 v2, v2
	v_rcp_f32_e32 v3, v3
	v_pk_fma_f32 v[0:1], v[36:37], v[36:37], 1.0 op_sel_hi:[1,1,0] neg_lo:[1,0,0] neg_hi:[1,0,0]
	s_nop 0
	v_max_f32_e32 v1, 0, v1
	v_max_f32_e32 v0, 0, v0
	v_sqrt_f32_e32 v0, v0
	v_sqrt_f32_e32 v1, v1
	s_nop 0
	v_pk_mul_f32 v[0:1], v[2:3], v[0:1]
	s_nop 0
	v_pk_mul_f32 v[34:35], v[4:5], v[0:1]
	v_pk_add_f32 v[0:1], v[114:115], v[38:39]
	v_pk_add_f32 v[2:3], v[116:117], v[22:23]
	v_pk_mul_f32 v[0:1], v[0:1], s[14:15] op_sel_hi:[1,0]
	v_pk_mul_f32 v[2:3], v[2:3], s[14:15] op_sel_hi:[1,0]
	v_exp_f32_e32 v0, v0
	v_exp_f32_e32 v1, v1
	v_exp_f32_e32 v2, v2
	v_exp_f32_e32 v3, v3
	v_pk_add_f32 v[0:1], v[0:1], 1.0 op_sel_hi:[1,0]
	s_nop 0
	v_rcp_f32_e32 v0, v0
	v_rcp_f32_e32 v1, v1
	v_pk_add_f32 v[2:3], v[2:3], 1.0 op_sel_hi:[1,0]
	v_pk_mul_f32 v[0:1], v[124:125], v[0:1]
	s_nop 0
	v_exp_f32_e32 v38, v0
	v_exp_f32_e32 v39, v1
	v_rcp_f32_e32 v2, v2
	v_rcp_f32_e32 v3, v3
	v_pk_fma_f32 v[0:1], v[38:39], v[38:39], 1.0 op_sel_hi:[1,1,0] neg_lo:[1,0,0] neg_hi:[1,0,0]
	s_nop 0
	v_max_f32_e32 v1, 0, v1
	v_max_f32_e32 v0, 0, v0
	v_sqrt_f32_e32 v0, v0
	v_sqrt_f32_e32 v1, v1
	s_nop 0
	v_pk_mul_f32 v[0:1], v[2:3], v[0:1]
	s_nop 0
	v_pk_mul_f32 v[32:33], v[6:7], v[0:1]
	v_pk_add_f32 v[0:1], v[114:115], v[40:41]
	v_pk_add_f32 v[2:3], v[116:117], v[24:25]
	v_pk_mul_f32 v[0:1], v[0:1], s[14:15] op_sel_hi:[1,0]
	v_pk_mul_f32 v[2:3], v[2:3], s[14:15] op_sel_hi:[1,0]
	v_exp_f32_e32 v0, v0
	v_exp_f32_e32 v1, v1
	v_exp_f32_e32 v2, v2
	v_exp_f32_e32 v3, v3
	v_pk_add_f32 v[0:1], v[0:1], 1.0 op_sel_hi:[1,0]
	s_nop 0
	v_rcp_f32_e32 v0, v0
	v_rcp_f32_e32 v1, v1
	v_pk_add_f32 v[2:3], v[2:3], 1.0 op_sel_hi:[1,0]
	v_pk_mul_f32 v[0:1], v[124:125], v[0:1]
	s_nop 0
	v_exp_f32_e32 v40, v0
	v_exp_f32_e32 v41, v1
	v_rcp_f32_e32 v2, v2
	v_rcp_f32_e32 v3, v3
	v_pk_fma_f32 v[0:1], v[40:41], v[40:41], 1.0 op_sel_hi:[1,1,0] neg_lo:[1,0,0] neg_hi:[1,0,0]
	s_nop 0
	v_max_f32_e32 v1, 0, v1
	v_max_f32_e32 v0, 0, v0
	v_sqrt_f32_e32 v0, v0
	v_sqrt_f32_e32 v1, v1
	s_nop 0
	v_pk_mul_f32 v[0:1], v[2:3], v[0:1]
	s_nop 0
	v_pk_mul_f32 v[24:25], v[8:9], v[0:1]
	v_pk_add_f32 v[0:1], v[114:115], v[42:43]
	v_pk_add_f32 v[2:3], v[116:117], v[26:27]
	v_pk_mul_f32 v[0:1], v[0:1], s[14:15] op_sel_hi:[1,0]
	v_pk_mul_f32 v[2:3], v[2:3], s[14:15] op_sel_hi:[1,0]
	v_exp_f32_e32 v0, v0
	v_exp_f32_e32 v1, v1
	v_exp_f32_e32 v2, v2
	v_exp_f32_e32 v3, v3
	v_pk_add_f32 v[0:1], v[0:1], 1.0 op_sel_hi:[1,0]
	s_nop 0
	v_rcp_f32_e32 v0, v0
	v_rcp_f32_e32 v1, v1
	v_pk_add_f32 v[2:3], v[2:3], 1.0 op_sel_hi:[1,0]
	v_pk_mul_f32 v[0:1], v[124:125], v[0:1]
	s_nop 0
	v_exp_f32_e32 v42, v0
	v_exp_f32_e32 v43, v1
	v_rcp_f32_e32 v2, v2
	v_rcp_f32_e32 v3, v3
	v_pk_fma_f32 v[0:1], v[42:43], v[42:43], 1.0 op_sel_hi:[1,1,0] neg_lo:[1,0,0] neg_hi:[1,0,0]
	s_nop 0
	v_max_f32_e32 v1, 0, v1
	v_max_f32_e32 v0, 0, v0
	v_sqrt_f32_e32 v0, v0
	v_sqrt_f32_e32 v1, v1
	s_nop 0
	v_pk_mul_f32 v[0:1], v[2:3], v[0:1]
	s_nop 0
	v_pk_mul_f32 v[26:27], v[10:11], v[0:1]
	v_pk_add_f32 v[0:1], v[114:115], v[44:45]
	v_pk_add_f32 v[2:3], v[116:117], v[28:29]
	v_pk_mul_f32 v[0:1], v[0:1], s[14:15] op_sel_hi:[1,0]
	v_pk_mul_f32 v[2:3], v[2:3], s[14:15] op_sel_hi:[1,0]
	v_exp_f32_e32 v0, v0
	v_exp_f32_e32 v1, v1
	v_exp_f32_e32 v2, v2
	v_exp_f32_e32 v3, v3
	v_pk_add_f32 v[0:1], v[0:1], 1.0 op_sel_hi:[1,0]
	s_nop 0
	v_rcp_f32_e32 v0, v0
	v_rcp_f32_e32 v1, v1
	v_pk_add_f32 v[2:3], v[2:3], 1.0 op_sel_hi:[1,0]
	v_pk_mul_f32 v[0:1], v[124:125], v[0:1]
	s_nop 0
	v_exp_f32_e32 v44, v0
	v_exp_f32_e32 v45, v1
	v_rcp_f32_e32 v2, v2
	v_rcp_f32_e32 v3, v3
	v_pk_fma_f32 v[0:1], v[44:45], v[44:45], 1.0 op_sel_hi:[1,1,0] neg_lo:[1,0,0] neg_hi:[1,0,0]
	s_nop 0
	v_max_f32_e32 v1, 0, v1
	v_max_f32_e32 v0, 0, v0
	v_sqrt_f32_e32 v0, v0
	v_sqrt_f32_e32 v1, v1
	s_nop 0
	v_pk_mul_f32 v[0:1], v[2:3], v[0:1]
	s_nop 0
	v_pk_mul_f32 v[28:29], v[12:13], v[0:1]
	v_pk_add_f32 v[0:1], v[114:115], v[46:47]
	v_pk_add_f32 v[2:3], v[116:117], v[30:31]
	v_pk_mul_f32 v[0:1], v[0:1], s[14:15] op_sel_hi:[1,0]
	v_pk_mul_f32 v[2:3], v[2:3], s[14:15] op_sel_hi:[1,0]
	v_exp_f32_e32 v0, v0
	v_exp_f32_e32 v1, v1
	v_exp_f32_e32 v2, v2
	v_exp_f32_e32 v3, v3
	v_pk_add_f32 v[0:1], v[0:1], 1.0 op_sel_hi:[1,0]
	s_nop 0
	v_rcp_f32_e32 v0, v0
	v_rcp_f32_e32 v1, v1
	v_pk_add_f32 v[2:3], v[2:3], 1.0 op_sel_hi:[1,0]
	v_pk_mul_f32 v[0:1], v[124:125], v[0:1]
	s_nop 0
	v_exp_f32_e32 v46, v0
	v_exp_f32_e32 v47, v1
	v_rcp_f32_e32 v2, v2
	v_rcp_f32_e32 v3, v3
	v_pk_fma_f32 v[0:1], v[46:47], v[46:47], 1.0 op_sel_hi:[1,1,0] neg_lo:[1,0,0] neg_hi:[1,0,0]
	s_nop 0
	v_max_f32_e32 v1, 0, v1
	v_max_f32_e32 v0, 0, v0
	v_sqrt_f32_e32 v0, v0
	v_sqrt_f32_e32 v1, v1
	s_nop 0
	v_pk_mul_f32 v[0:1], v[2:3], v[0:1]
	s_nop 0
	v_pk_mul_f32 v[30:31], v[14:15], v[0:1]

; template <int DIR>
; __device__ __forceinline__ void lru_dir(const bf16_t* XR, const bf16_t* GATE, bf16_t* YP, u32x4* HSF, const bf16_t* bdw_dir, float bias_r, float bias_i, float sp,
;                                         int b, int n2, int lane, int wave, LAS float* xl) {
;     ...
;         for (int k = 0; k < 2; ++k) {
;             if (valid[k]) {
;                 const float val = Hl[k] + Pl[k] * hcar, got = __shfl_xor(val, 32);
;                 float hcur = first ? hcar : got;
;                 f32x16 hs;
; #pragma unroll
;                 for (int rr = 0; rr < 16; ++rr) { const int r = DIR == 0 ? rr : 15 - rr; hcur = av[k][r] * hcur + bv[k][r]; hs[r] = hcur; }
;                 const float got2 = __shfl_xor(hcur, 32);
;                 hcar = first ? got2 : hcur;
;                 const int tg = trow[k] < ML ? (trow[k] >> 12) * 136 + 8 + ((trow[k] & (SEQ - 1)) >> 5) : b * 136 + ((trow[k] - ML - b * CTXL) >> 5);
;                 u32x4* hp = HSF + (((size_t)tg * 32 + n2) * 64 + lane) * 2;
;                 if (DIR == 0) {
;                     u32x4 w0, w1;
;                     w0.x = pk2(hs[0], hs[1]); w0.y = pk2(hs[2], hs[3]); w0.z = pk2(hs[4], hs[5]); w0.w = pk2(hs[6], hs[7]);
;                     w1.x = pk2(hs[8], hs[9]); w1.y = pk2(hs[10], hs[11]); w1.z = pk2(hs[12], hs[13]); w1.w = pk2(hs[14], hs[15]);
;                     hp[0] = w0; hp[1] = w1;
;                 } else {
;                     const u32x4 w0 = hp[0], w1 = hp[1];
;                     const unsigned hw[8] = {w0.x, w0.y, w0.z, w0.w, w1.x, w1.y, w1.z, w1.w};
;                     const bf16_t* gp = GATE + (size_t)(trow[k] + tau) * DM + chcol + 8 * hh;
;                     const bf16x8 G0 = *(const bf16x8*)gp, G1 = *(const bf16x8*)(gp + 16);
;                     f32x16 gv;
; #pragma unroll
;                     for (int r = 0; r < 16; ++r) gv[r] = 0.f;
;                     gv = mfma32(G0, I0, gv); gv = mfma32(G1, I1, gv);
;                     bf16_t* yp = YP + (size_t)(trow[k] + 16 * hh) * DM + chcol + e;
; #pragma unroll
;                     for (int r = 0; r < 16; ++r) { const float x = gv[r], u2 = 1.5957691216f * (x + 0.044715f * x * x * x);
;                         const float hf = (r & 1) ? bfhi(hw[r >> 1]) : bflo(hw[r >> 1]);
;                         const float y = (hf + hs[r]) * x * sigmoidf_(u2);
;                         yp[(size_t)r * DM] = (bf16_t)f2bf(y); }
.LBB0_59:
	s_ashr_i32 s3, s2, 31
	s_lshl_b64 s[2:3], s[2:3], 16
	s_waitcnt lgkmcnt(0)
	v_cndmask_b32_e64 v170, v0, v138, s[40:41]
	v_lshl_add_u64 v[0:1], v[112:113], 0, s[2:3]
	v_mov_b32_e32 v16, v184
	v_mov_b32_e32 v17, v185
	v_mov_b32_e32 v18, v186
	v_mov_b32_e32 v19, v187
	v_mov_b32_e32 v20, v188
	v_mov_b32_e32 v21, v189
	v_mov_b32_e32 v22, v190
	v_mov_b32_e32 v23, v191
	v_lshlrev_b64 v[0:1], 11, v[132:133]
	v_lshl_add_u64 v[4:5], v[120:121], 0, v[0:1]
	v_mov_b32_e32 v0, v192
	v_mov_b32_e32 v1, v193
	v_mov_b32_e32 v2, v194
	v_mov_b32_e32 v3, v195
	v_mov_b32_e32 v156, v196
	v_mov_b32_e32 v157, v197
	v_mov_b32_e32 v158, v198
	v_mov_b32_e32 v159, v199
	v_or_b32_e32 v98, s36, v102
	v_ashrrev_i32_e32 v99, 31, v98
	v_lshlrev_b64 v[98:99], 11, v[98:99]
	v_lshl_add_u64 v[98:99], v[122:123], 0, v[98:99]
	s_movk_i32 s2, 0x1000
	v_mfma_f32_32x32x16_bf16 v[0:15], v[0:3], v[58:61], 0
	v_lshlrev_b32_e32 v132, 16, v20
	v_add_f32_e32 v132, v138, v132
	v_and_b32_e32 v20, 0xffff0000, v20
	v_add_f32_e32 v20, v139, v20
	v_mfma_f32_32x32x16_bf16 v[0:15], v[156:159], v[62:65], v[0:15]
	s_nop 11
	v_mul_f32_e32 v111, 0x3d372713, v0
	v_mul_f32_e32 v111, v0, v111
	v_fma_f32 v111, v0, v111, v0
	v_mul_f32_e32 v111, 0x3fcc422a, v111
	v_mul_f32_e32 v111, 0xbfb8aa3b, v111
	v_exp_f32_e32 v111, v111
	v_mul_f32_e32 v0, v132, v0
	v_add_f32_e32 v111, 1.0, v111
	v_rcp_f32_e32 v111, v111
	s_nop 0
	v_mul_f32_e32 v0, v0, v111
	v_cvt_pk_bf16_f32 v0, v0, v49
	global_store_short v[98:99], v0, off
	v_mul_f32_e32 v0, 0x3d372713, v1
	v_mul_f32_e32 v0, v1, v0
	v_fma_f32 v0, v1, v0, v1
	v_mul_f32_e32 v0, 0x3fcc422a, v0
	v_mul_f32_e32 v0, 0xbfb8aa3b, v0
	v_exp_f32_e32 v0, v0
	v_mul_f32_e32 v1, v20, v1
	v_and_b32_e32 v20, 0xffff0000, v21
	v_add_f32_e32 v20, v135, v20
	v_add_f32_e32 v0, 1.0, v0
	v_rcp_f32_e32 v0, v0
	s_nop 0
	v_mul_f32_e32 v0, v1, v0
	v_cvt_pk_bf16_f32 v0, v0, v49
	global_store_short v[98:99], v0, off offset:2048
	v_mul_f32_e32 v0, 0x3d372713, v2
	v_mul_f32_e32 v0, v2, v0
	v_fma_f32 v0, v2, v0, v2
	v_mul_f32_e32 v0, 0x3fcc422a, v0
	v_mul_f32_e32 v0, 0xbfb8aa3b, v0
	v_exp_f32_e32 v0, v0
	v_lshlrev_b32_e32 v1, 16, v21
	v_add_f32_e32 v1, v134, v1
	v_mul_f32_e32 v1, v1, v2
	v_add_f32_e32 v0, 1.0, v0
	v_rcp_f32_e32 v0, v0
	s_nop 0
	v_mul_f32_e32 v0, v1, v0
	v_cvt_pk_bf16_f32 v2, v0, v49
	v_add_co_u32_e32 v0, vcc, s2, v98
	s_movk_i32 s2, 0x3000
	s_nop 0
	v_addc_co_u32_e32 v1, vcc, 0, v99, vcc
	v_add_co_u32_e32 v132, vcc, s76, v98
	s_nop 1
	v_addc_co_u32_e32 v133, vcc, 0, v99, vcc
	global_store_short v[132:133], v2, off offset:-4096
	v_mul_f32_e32 v2, 0x3d372713, v3
	v_mul_f32_e32 v2, v3, v2
	v_fma_f32 v2, v3, v2, v3
	v_mul_f32_e32 v2, 0x3fcc422a, v2
	v_mul_f32_e32 v2, 0xbfb8aa3b, v2
	v_exp_f32_e32 v2, v2
	v_mul_f32_e32 v3, v20, v3
	v_add_f32_e32 v2, 1.0, v2
	v_rcp_f32_e32 v2, v2
	s_nop 0
	v_mul_f32_e32 v2, v3, v2
	v_cvt_pk_bf16_f32 v2, v2, v49
	global_store_short v[0:1], v2, off offset:2048
	v_mul_f32_e32 v0, 0x3d372713, v4
	v_mul_f32_e32 v0, v4, v0
	v_fma_f32 v0, v4, v0, v4
	v_mul_f32_e32 v0, 0x3fcc422a, v0
	v_mul_f32_e32 v0, 0xbfb8aa3b, v0
	v_exp_f32_e32 v0, v0
	v_lshlrev_b32_e32 v1, 16, v22
	v_add_f32_e32 v1, v136, v1
	v_mul_f32_e32 v1, v1, v4
	v_add_f32_e32 v0, 1.0, v0
	v_rcp_f32_e32 v0, v0
	s_nop 0
	v_mul_f32_e32 v0, v1, v0
	v_cvt_pk_bf16_f32 v0, v0, v49
	global_store_short v[132:133], v0, off
	v_mul_f32_e32 v0, 0x3d372713, v5
	v_mul_f32_e32 v0, v5, v0
	v_fma_f32 v0, v5, v0, v5
	v_mul_f32_e32 v0, 0x3fcc422a, v0
	v_mul_f32_e32 v0, 0xbfb8aa3b, v0
	v_exp_f32_e32 v0, v0
	v_and_b32_e32 v1, 0xffff0000, v22
	v_add_f32_e32 v1, v137, v1
	v_mul_f32_e32 v1, v1, v5
	v_add_f32_e32 v0, 1.0, v0
	v_rcp_f32_e32 v0, v0
	v_and_b32_e32 v5, 0xffff0000, v23
	v_add_f32_e32 v5, v129, v5
	v_mul_f32_e32 v5, v5, v7
	v_mul_f32_e32 v0, v1, v0
	v_cvt_pk_bf16_f32 v0, v0, v49
	global_store_short v[132:133], v0, off offset:2048
	v_mul_f32_e32 v0, 0x3d372713, v6
	v_mul_f32_e32 v0, v6, v0
	v_fma_f32 v0, v6, v0, v6
	v_mul_f32_e32 v0, 0x3fcc422a, v0
	v_mul_f32_e32 v0, 0xbfb8aa3b, v0
	v_exp_f32_e32 v0, v0
	v_lshlrev_b32_e32 v1, 16, v23
	v_add_f32_e32 v1, v128, v1
	v_mul_f32_e32 v1, v1, v6
	v_add_f32_e32 v0, 1.0, v0
	v_rcp_f32_e32 v0, v0
	s_nop 0
	v_mul_f32_e32 v0, v1, v0
	v_cvt_pk_bf16_f32 v4, v0, v49
	v_add_co_u32_e32 v0, vcc, s2, v98
; __device__ __forceinline__ unsigned f2bf(float f) { return pk2(f, 0.0f) & 0xffffu; }
; __device__ __forceinline__ float bflo(unsigned w) { return __uint_as_float(w << 16); }
; __device__ __forceinline__ float bfhi(unsigned w) { return __uint_as_float(w & 0xffff0000u); }
; __device__ __forceinline__ float sigmoidf_(float x) { return __builtin_amdgcn_rcpf(1.0f + __builtin_amdgcn_exp2f(x * -1.4426950408889634f)); }
; template <int DIR>
; __device__ __forceinline__ void lru_dir(const bf16_t* XR, const bf16_t* GATE, bf16_t* YP, u32x4* HSF, const bf16_t* bdw_dir, float bias_r, float bias_i, float sp,
;                                         int b, int n2, int lane, int wave, LAS float* xl) {
;     ...
;                     bf16_t* yp = YP + (size_t)(trow[k] + 16 * hh) * DM + chcol + e;
; #pragma unroll
;                     for (int r = 0; r < 16; ++r) { const float x = gv[r], u2 = 1.5957691216f * (x + 0.044715f * x * x * x);
;                         const float hf = (r & 1) ? bfhi(hw[r >> 1]) : bflo(hw[r >> 1]);
;                         const float y = (hf + hs[r]) * x * sigmoidf_(u2);
;                         yp[(size_t)r * DM] = (bf16_t)f2bf(y); }
	s_movk_i32 s2, 0x4000
	s_nop 0
	v_addc_co_u32_e32 v1, vcc, 0, v99, vcc
	v_add_co_u32_e32 v2, vcc, s2, v98
	s_movk_i32 s2, 0x5000
	s_nop 0
	v_addc_co_u32_e32 v3, vcc, 0, v99, vcc
	global_store_short v[2:3], v4, off offset:-4096
	v_mul_f32_e32 v4, 0x3d372713, v7
	v_mul_f32_e32 v4, v7, v4
	v_fma_f32 v4, v7, v4, v7
	v_mul_f32_e32 v4, 0x3fcc422a, v4
	v_mul_f32_e32 v4, 0xbfb8aa3b, v4
	v_exp_f32_e32 v4, v4
	s_nop 0
	v_add_f32_e32 v4, 1.0, v4
	v_rcp_f32_e32 v4, v4
	s_nop 0
	v_mul_f32_e32 v4, v5, v4
	v_cvt_pk_bf16_f32 v4, v4, v49
	global_store_short v[0:1], v4, off offset:2048
	v_mul_f32_e32 v0, 0x3d372713, v8
	v_mul_f32_e32 v0, v8, v0
	v_fma_f32 v0, v8, v0, v8
	v_mul_f32_e32 v0, 0x3fcc422a, v0
	v_mul_f32_e32 v0, 0xbfb8aa3b, v0
	v_exp_f32_e32 v0, v0
	v_lshlrev_b32_e32 v1, 16, v16
	v_add_f32_e32 v1, v130, v1
	v_mul_f32_e32 v1, v1, v8
	v_add_f32_e32 v0, 1.0, v0
	v_rcp_f32_e32 v0, v0
	v_and_b32_e32 v5, 0xffff0000, v17
	v_add_f32_e32 v5, v147, v5
	v_mul_f32_e32 v5, v5, v11
	v_mul_f32_e32 v0, v1, v0
	v_cvt_pk_bf16_f32 v0, v0, v49
	global_store_short v[2:3], v0, off
	v_mul_f32_e32 v0, 0x3d372713, v9
	v_mul_f32_e32 v0, v9, v0
	v_fma_f32 v0, v9, v0, v9
	v_mul_f32_e32 v0, 0x3fcc422a, v0
	v_mul_f32_e32 v0, 0xbfb8aa3b, v0
	v_exp_f32_e32 v0, v0
	v_and_b32_e32 v1, 0xffff0000, v16
	v_add_f32_e32 v1, v131, v1
	v_mul_f32_e32 v1, v1, v9
	v_add_f32_e32 v0, 1.0, v0
	v_rcp_f32_e32 v0, v0
	s_nop 0
	v_mul_f32_e32 v0, v1, v0
	v_cvt_pk_bf16_f32 v0, v0, v49
	global_store_short v[2:3], v0, off offset:2048
	v_mul_f32_e32 v0, 0x3d372713, v10
	v_mul_f32_e32 v0, v10, v0
	v_fma_f32 v0, v10, v0, v10
	v_mul_f32_e32 v0, 0x3fcc422a, v0
	v_mul_f32_e32 v0, 0xbfb8aa3b, v0
	v_exp_f32_e32 v0, v0
	v_lshlrev_b32_e32 v1, 16, v17
	v_add_f32_e32 v1, v146, v1
	v_mul_f32_e32 v1, v1, v10
	v_add_f32_e32 v0, 1.0, v0
	v_rcp_f32_e32 v0, v0
	s_nop 0
	v_mul_f32_e32 v0, v1, v0
	v_cvt_pk_bf16_f32 v4, v0, v49
	v_add_co_u32_e32 v0, vcc, s2, v98
	s_movk_i32 s2, 0x7000
	s_nop 0
	v_addc_co_u32_e32 v1, vcc, 0, v99, vcc
	v_add_co_u32_e32 v2, vcc, s4, v98
	s_nop 1
	v_addc_co_u32_e32 v3, vcc, 0, v99, vcc
	global_store_short v[2:3], v4, off offset:-4096
	v_mul_f32_e32 v4, 0x3d372713, v11
	v_mul_f32_e32 v4, v11, v4
	v_fma_f32 v4, v11, v4, v11
	v_mul_f32_e32 v4, 0x3fcc422a, v4
	v_mul_f32_e32 v4, 0xbfb8aa3b, v4
	v_exp_f32_e32 v4, v4
	s_nop 0
	v_add_f32_e32 v4, 1.0, v4
	v_rcp_f32_e32 v4, v4
	s_nop 0
	v_mul_f32_e32 v4, v5, v4
	v_cvt_pk_bf16_f32 v4, v4, v49
	global_store_short v[0:1], v4, off offset:2048
	v_mul_f32_e32 v0, 0x3d372713, v12
	v_mul_f32_e32 v0, v12, v0
	v_fma_f32 v0, v12, v0, v12
	v_mul_f32_e32 v0, 0x3fcc422a, v0
	v_mul_f32_e32 v0, 0xbfb8aa3b, v0
	v_exp_f32_e32 v0, v0
	v_lshlrev_b32_e32 v1, 16, v18
	v_add_f32_e32 v1, v148, v1
	v_mul_f32_e32 v1, v1, v12
	v_add_f32_e32 v0, 1.0, v0
	v_rcp_f32_e32 v0, v0
	s_nop 0
	v_mul_f32_e32 v0, v1, v0
	v_cvt_pk_bf16_f32 v0, v0, v49
	global_store_short v[2:3], v0, off
	v_mul_f32_e32 v0, 0x3d372713, v13
	v_mul_f32_e32 v0, v13, v0
	v_fma_f32 v0, v13, v0, v13
	v_mul_f32_e32 v0, 0x3fcc422a, v0
	v_mul_f32_e32 v0, 0xbfb8aa3b, v0
	v_exp_f32_e32 v0, v0
	v_and_b32_e32 v1, 0xffff0000, v18
	v_add_f32_e32 v1, v149, v1
	v_mul_f32_e32 v1, v1, v13
	v_add_f32_e32 v0, 1.0, v0
	v_rcp_f32_e32 v0, v0
	s_nop 0
	v_mul_f32_e32 v0, v1, v0
	v_cvt_pk_bf16_f32 v0, v0, v49
	global_store_short v[2:3], v0, off offset:2048
	v_mul_f32_e32 v0, 0x3d372713, v14
	v_mul_f32_e32 v0, v14, v0
	v_fma_f32 v0, v14, v0, v14
	v_mul_f32_e32 v0, 0x3fcc422a, v0
	v_mul_f32_e32 v0, 0xbfb8aa3b, v0
	v_exp_f32_e32 v0, v0
	v_lshlrev_b32_e32 v1, 16, v19
	v_add_f32_e32 v1, v150, v1
	v_mul_f32_e32 v1, v1, v14
	v_add_f32_e32 v0, 1.0, v0
	v_rcp_f32_e32 v0, v0
	v_and_b32_e32 v3, 0xffff0000, v19
	v_add_f32_e32 v3, v151, v3
	v_mul_f32_e32 v3, v3, v15
	v_mul_f32_e32 v0, v1, v0
	v_cvt_pk_bf16_f32 v2, v0, v49
	v_add_co_u32_e32 v0, vcc, s2, v98
	s_nop 1
	v_addc_co_u32_e32 v1, vcc, 0, v99, vcc
	global_store_short v[0:1], v2, off
	v_mul_f32_e32 v2, 0x3d372713, v15
	v_mul_f32_e32 v2, v15, v2
	v_fma_f32 v2, v15, v2, v15
	v_mul_f32_e32 v2, 0x3fcc422a, v2
	v_mul_f32_e32 v2, 0xbfb8aa3b, v2
	v_exp_f32_e32 v2, v2
	s_nop 0
	v_add_f32_e32 v2, 1.0, v2
	v_rcp_f32_e32 v2, v2
	s_nop 0
	v_mul_f32_e32 v2, v3, v2
	v_cvt_pk_bf16_f32 v2, v2, v49
	global_store_short v[0:1], v2, off offset:2048

; __global__ void __launch_bounds__(512, 2) fwd_kernel(Args a) {
	.amdhsa_kernel _Z10fwd_kernel4Args
		.amdhsa_group_segment_fixed_size 0
		.amdhsa_private_segment_fixed_size 0
		.amdhsa_kernarg_size 488
		.amdhsa_user_sgpr_count 2
		.amdhsa_user_sgpr_dispatch_ptr 0
		.amdhsa_user_sgpr_queue_ptr 0
		.amdhsa_user_sgpr_kernarg_segment_ptr 1
		.amdhsa_user_sgpr_dispatch_id 0
		.amdhsa_user_sgpr_kernarg_preload_length 0
		.amdhsa_user_sgpr_kernarg_preload_offset 0
		.amdhsa_user_sgpr_private_segment_size 0
		.amdhsa_uses_dynamic_stack 0
		.amdhsa_enable_private_segment 0
		.amdhsa_system_sgpr_workgroup_id_x 1
		.amdhsa_system_sgpr_workgroup_id_y 0
		.amdhsa_system_sgpr_workgroup_id_z 0
		.amdhsa_system_sgpr_workgroup_info 0
		.amdhsa_system_vgpr_workitem_id 2
		.amdhsa_next_free_vgpr 256
		.amdhsa_next_free_sgpr 100
		.amdhsa_accum_offset 256
		.amdhsa_reserve_vcc 1
		.amdhsa_float_round_mode_32 0
		.amdhsa_float_round_mode_16_64 0
		.amdhsa_float_denorm_mode_32 3
		.amdhsa_float_denorm_mode_16_64 3
		.amdhsa_dx10_clamp 1
		.amdhsa_ieee_mode 1
		.amdhsa_fp16_overflow 0
		.amdhsa_tg_split 0
		.amdhsa_exception_fp_ieee_invalid_op 0
		.amdhsa_exception_fp_denorm_src 0
		.amdhsa_exception_fp_ieee_div_zero 0
		.amdhsa_exception_fp_ieee_overflow 0
		.amdhsa_exception_fp_ieee_underflow 0
		.amdhsa_exception_fp_ieee_inexact 0
		.amdhsa_exception_int_div_zero 0
	.end_amdhsa_kernel

; __global__ void __launch_bounds__(512, 2) fwd_kernel(Args a) {
amdhsa.kernels:
  - .agpr_count:     0
    .args:
      - .offset:         0
        .size:           232
        .value_kind:     by_value
      - .offset:         232
        .size:           4
        .value_kind:     hidden_block_count_x
      - .offset:         236
        .size:           4
        .value_kind:     hidden_block_count_y
      - .offset:         240
        .size:           4
        .value_kind:     hidden_block_count_z
      - .offset:         244
        .size:           2
        .value_kind:     hidden_group_size_x
      - .offset:         246
        .size:           2
        .value_kind:     hidden_group_size_y
      - .offset:         248
        .size:           2
        .value_kind:     hidden_group_size_z
      - .offset:         250
        .size:           2
        .value_kind:     hidden_remainder_x
      - .offset:         252
        .size:           2
        .value_kind:     hidden_remainder_y
      - .offset:         254
        .size:           2
        .value_kind:     hidden_remainder_z
      - .offset:         272
        .size:           8
        .value_kind:     hidden_global_offset_x
      - .offset:         280
        .size:           8
        .value_kind:     hidden_global_offset_y
      - .offset:         288
        .size:           8
        .value_kind:     hidden_global_offset_z
      - .offset:         296
        .size:           2
        .value_kind:     hidden_grid_dims
      - .offset:         320
        .size:           8
        .value_kind:     hidden_multigrid_sync_arg
      - .offset:         352
        .size:           4
        .value_kind:     hidden_dynamic_lds_size
    .group_segment_fixed_size: 0
    .kernarg_segment_align: 8
    .kernarg_segment_size: 488
    .language:       OpenCL C
    .language_version:
      - 2
      - 0
    .max_flat_workgroup_size: 512
    .name:           _Z10fwd_kernel4Args
    .private_segment_fixed_size: 0
    .sgpr_count:     106
    .sgpr_spill_count: 142
    .symbol:         _Z10fwd_kernel4Args.kd
    .uniform_work_group_size: 1
    .uses_dynamic_stack: false
    .vgpr_count:     256
    .vgpr_spill_count: 0
    .wavefront_size: 64
